# diff-attention: static s_setprio 1 for waves 4-7 during the unit
# baseline (speedup 1.0000x reference)
; template <int THRL> ...
;   int tid_ = threadIdx.x; asm volatile("" : "+v"(tid_));
;   const int tid = tid_, lane = tid & 63, r32 = lane & 31, hi = lane >> 5; const int wid = __builtin_amdgcn_readfirstlane(tid >> 6);
;   const long tok0 = (long)b * SEQ;
;   const unsigned lds0 = (unsigned)(uintptr_t)shm;
;   float* wsf = (float*)(shm + LDS_WS) + wid * 64;
;   const bf16* vsrc = VB + ((size_t)(b * 8 + h) * 64 * 16 + 2 * wid) * 512 + lane * 8;
;   const unsigned kdst = lds0 + LDS_K + wid * 1024, vdst = lds0 + LDS_V + wid * 2048;
;   const lds_cptr shm3 = (lds_cptr)shm;
;   const lds_cptr kp0 = shm3 + LDS_K + hi * 1024 + r32 * 16;
;   const lds_cptr vp0 = shm3 + LDS_V + ((lane >> 4) & 1) * 32 + (lane & 3) * 8 + (4 * hi + ((lane & 15) >> 2)) * 64;
;   const lds_cptr qp0 = shm3 + LDS_Q + wid * 4096 + lane * 16;
;   int sj = 0; bool sjp = false, sji = false;
;   if (SJ.n > 0) { *(pg8::f32x4*)(shm + att::LDS_SJ_G + tid * 16) = *(const pg8::f32x4*)(SJ.g_mlp + tid * 4); }
;     ...
;   for (int c = 0; c < 2; ++c) {
;     const bf16* Qw = proj + (tok0 + qb * 256 + wid * QBLK + r32) * LDP + h * 128 + c * 64 + hi * 8;
;     const bf16* ksrc = KB + ((size_t)((b * 8 + h) * 2 + c) * 64 * 8 + wid) * 512 + lane * 8;
.LBB0_401:
	s_ashr_i32 s24, s0, 6
	s_cmp_lt_u32 s24, 4
	s_cbranch_scc1 .Lda_prio_skip
	s_setprio 1
.Lda_prio_skip:
	s_and_b32 s0, s0, 0x3fffffc0
	s_ashr_i32 s26, s79, 7
	s_lshl_b32 s0, s0, 2
	s_bfe_u32 s2, s79, 0x30004
	s_add_i32 s80, s0, 0
	s_lshl_b32 s0, s26, 3
	s_or_b32 s20, s0, s2
	s_ashr_i32 s27, s26, 31
	s_ashr_i32 s21, s20, 31
	s_lshl_b32 s30, s24, 1
	s_lshl_b32 s40, s2, 1
	s_and_b32 s41, s79, 15
	s_lshl_b64 s[6:7], s[26:27], 12
	s_add_i32 s80, s80, 0x1c000
	s_ashr_i32 s31, s30, 31
	s_lshl_b64 s[28:29], s[20:21], 20
	s_add_u32 s0, s10, s28
	s_addc_u32 s21, s11, s29
	s_lshl_b64 s[30:31], s[30:31], 10
	s_add_u32 s34, s0, s30
	s_addc_u32 s35, s21, s31
	s_lshl_b32 s81, s24, 10
	s_cmp_lg_u32 0, -1
	s_cselect_b32 s0, 0, 0
	s_lshl_b32 s96, s24, 11
	s_add_i32 s89, s81, s0
	s_add_i32 s0, s0, s96
	s_add_i32 s97, s0, 0x8000
	s_lshl_b32 s0, s24, 12
	v_and_b32_e32 v189, 31, v2
	v_bfe_u32 v190, v2, 5, 1
	s_add_i32 s77, s0, 0
	s_lshl_b32 s0, s41, 8
	v_and_b32_e32 v188, 63, v2
	v_lshlrev_b32_e32 v4, 10, v190
	v_lshlrev_b32_e32 v5, 4, v189
	s_or_b32 s0, s6, s0
	s_lshl_b32 s6, s24, 5
	v_lshlrev_b32_e32 v148, 4, v188
	v_mov_b32_e32 v149, v147
	v_add3_u32 v191, 0, v4, v5
	v_lshlrev_b32_e32 v4, 1, v2
	v_lshlrev_b32_e32 v5, 3, v2
	s_add_i32 s77, s77, 0x14000
	s_ashr_i32 s21, s6, 31
	v_lshl_add_u64 v[150:151], s[34:35], 0, v[148:149]
	v_and_b32_e32 v4, 32, v4
	v_and_b32_e32 v5, 24, v5
	s_add_u32 s34, s0, s6
	v_add3_u32 v4, 0, v4, v5
	v_lshlrev_b32_e32 v5, 8, v190
	v_and_b32_e32 v3, 0xc0, v3
	s_addc_u32 s35, s7, s21
	v_add3_u32 v192, v4, v5, v3
	v_or_b32_e32 v4, s34, v189
	v_mov_b32_e32 v5, s35
	s_ashr_i32 s25, s24, 31
	v_lshlrev_b64 v[4:5], 13, v[4:5]
	s_lshl_b32 s0, s2, 8
	s_lshl_b32 s50, s20, 1
	s_lshl_b64 s[36:37], s[24:25], 10
	v_lshl_add_u64 v[4:5], s[70:71], 0, v[4:5]
	s_add_u32 s6, s8, s36
	v_lshl_add_u64 v[4:5], v[4:5], 0, s[0:1]
	v_lshlrev_b32_e32 v152, 4, v190
	v_mov_b32_e32 v153, v147
	s_addc_u32 s7, s9, s37
	v_bfe_u32 v3, v2, 4, 2
	v_lshl_add_u64 v[154:155], v[4:5], 0, v[152:153]
	s_add_u32 s0, s92, s0
	v_lshl_or_b32 v153, s24, 3, v3
	v_bitop3_b32 v3, s24, v2, 15 bitop3:0x78
	s_addc_u32 s2, s93, 0
	v_lshlrev_b32_e32 v195, 2, v3
	v_and_b32_e32 v3, 7, v2
	s_add_i32 s21, 0, 0x24800
	v_lshl_add_u32 v200, v3, 5, s21
	s_lshl_b32 s20, s20, 7
	s_lshl_b32 s21, s41, 3
	s_or_b32 s20, s20, s21
	s_add_i32 s20, s20, s24
	s_ashr_i32 s21, s20, 31
	s_lshl_b64 s[20:21], s[20:21], 14
	s_add_u32 s20, s68, s20
	s_addc_u32 s21, s69, s21
	s_lshl_b32 s24, s24, 13
	s_add_i32 s51, s24, 0
	s_lshl_b64 s[24:25], s[34:35], 12
	s_add_u32 s24, s0, s24
	s_addc_u32 s25, s2, s25
	s_add_u32 s34, s44, s36
	s_addc_u32 s35, s45, s37
	s_lshl_b32 s0, s26, 4
	s_or_b32 s72, s0, s40
	s_mov_b64 s[38:39], 0xf8000
	s_add_u32 s0, s28, s30
	v_ashrrev_i32_e32 v197, 3, v2
	v_ashrrev_i32_e32 v5, 5, v2
	v_lshl_add_u64 v[164:165], v[150:151], 0, s[38:39]
	s_mov_b64 s[38:39], 0xf8400
	s_addc_u32 s2, s29, s31
	v_bitop3_b32 v2, v5, v2, 7 bitop3:0x78
	v_lshlrev_b32_e32 v5, 2, v197
	v_lshl_add_u64 v[166:167], v[150:151], 0, s[38:39]
	s_mov_b64 s[38:39], 0xfc000
	s_add_u32 s26, s46, s0
	v_lshl_add_u64 v[156:157], s[6:7], 0, v[148:149]
	s_mov_b64 s[6:7], 0x4400
	v_lshl_add_u32 v4, v3, 11, s48
	v_lshlrev_b32_e32 v2, 4, v2
	v_and_b32_e32 v5, 12, v5
	v_lshl_add_u64 v[168:169], v[150:151], 0, s[38:39]
	s_mov_b64 s[38:39], 0xfc400
	s_addc_u32 s27, s47, s2
	s_mov_b32 s88, 0
	v_add_u32_e32 v193, 0x8000, v192
	v_lshl_add_u64 v[158:159], v[150:151], 0, s[14:15]
	v_lshl_add_u64 v[160:161], v[150:151], 0, s[16:17]
	v_lshl_add_u64 v[162:163], v[150:151], 0, s[6:7]
	v_cmp_gt_u32_e64 s[6:7], 32, v188
	v_lshl_add_u32 v196, v189, 2, s80
	v_add3_u32 v198, v4, v2, v5
	v_lshlrev_b32_e32 v199, 3, v3
	v_lshl_add_u64 v[170:171], v[150:151], 0, s[38:39]
	v_lshl_add_u64 v[172:173], s[34:35], 0, v[148:149]
	v_lshl_add_u64 v[174:175], s[26:27], 0, v[148:149]
	s_mov_b64 s[26:27], -1
	s_mov_b32 s2, 0
	s_branch .LBB0_403

; __device__ __forceinline__ int v_st(int k, int c) { const int kk = (k & ~0xC) | ((k & 4) << 1) | ((k & 8) >> 1); return ((kk >> 3) * 4 + (c >> 5)) * 512 + ((kk & 7) * 32 + (c & 31)) * 2; }
; template <int VAR> __device__ __forceinline__ void na_unit(const bf16* __restrict__ proj, bf16* mix, const float* __restrict__ relb, int b, int h, int rg, char* lds) {
;     ...
;   float* ws = (float*)(lds + LDS_WS) + wid * 64; float* li_l = ws; float* al_l = ws + 32;
;   float* bl = (float*)(lds + LDS_BIAS);
;   const long tok0 = (long)b * SEQ;
;   const int r0 = rg * 4, gr = r0 + (wid >> 1), cq = 32 * (wid & 1) + r32;
;   const int jlo = min(max(r0 - 4, 0), 56), jhi = min(max(r0 - 1, 0), 56) + 7, NT = (VAR == 1) ? 1 : jhi - jlo + 1;
;   const int mlo = min(max(gr - 4, 0), 56);
;   const int cs = min(max(cq - 8, 0), 48);
;   const int mbase = 4 * hi - cs;
;   const char* blane0 = (const char*)(bl + 48 + 15 - cq + 4 * hi);
;   const int sr = tid >> 4, sc = (tid & 15) * 8, vst0 = v_st(sr, sc), vst1 = v_st(32 + sr, sc), kst0 = KSWZ128(sr, sc * 2), kst1 = KSWZ128(32 + sr, sc * 2);
;   const int vb0 = (int)(uintptr_t)V_lds + v_rd_base(lane);
;   const bf16* Kh = proj + tok0 * LDP + 2048 + h * 128;
;   const bf16* Vh = proj + tok0 * LDP + 3072 + h * 128;
;   const bf16* Qw = proj + (tok0 + gr * 64 + cq) * LDP + 1024 + h * 128 + hi * 8;
;   __syncthreads();
;   for (int i = tid; i < 15 * NA_BSTRIDE; i += 512) { const int ri = i >> 7, ci = (i & 127) - 48; bl[i] = (ci >= 0 && ci < 31) ? relb[(h * 15 + ri) * 31 + ci] * 1.4426950408889634f : 0.f; }
;   char* Ql = lds + LDS_NAQ + wid * 8192 + lane * 16;
;   { bf16x8 qr[8];
; #pragma unroll
;     for (int d0 = 0; d0 < 8; ++d0) qr[d0] = ld8(Qw + d0 * 16);
; #pragma unroll
;     for (int d0 = 0; d0 < 8; ++d0) *(bf16x8*)(Ql + d0 * 1024) = qr[d0]; }
;   float zf_ = 0.f; asm volatile("" : "+v"(zf_));
;   f32x16 zv_;
; #pragma unroll
;   for (int r = 0; r < 16; ++r) zv_[r] = zf_;
;   float m_reg = -1e30f, l_reg = 0; f32x16 o[4]; o[0] = zv_; o[1] = zv_; o[2] = zv_; o[3] = zv_;
; __global__ void __launch_bounds__(NWAVES * 64, 2) mega_fwd(Args args) {
;     ...
;         for (int u = vcu; u < BATCH * NHEAD * 16; u += G) {
;             const int bh = u >> 4, rg = u & 15;
;             att::na_unit<0>(PROJ, MIX, relb, bh >> 3, bh & 7, rg, (char*)lds + RING_OFF);
.LBB0_506:
	s_setprio 0
	s_lshl_b32 s3, s76, 2
	s_lshl_b32 s50, s33, 2
	v_mov_b32_e32 v147, 0
	s_mov_b32 s59, 0
	s_add_i32 s65, 0, 0x10800
	s_mov_b32 s88, 0x41000000
	s_mov_b64 s[60:61], 0x100000
	v_mov_b32_e32 v1, 0xf149f2ca
	s_mov_b32 s89, s76
	v_writelane_b32 v242, s50, 23
	s_branch .LBB0_508
